# FoX softmax: all 32 s-m pairs packed (v_pk_add_f32) and the 16-long serial row-sum add chains replaced by v_pk_add_f32 trees (9-10 instrs, depth 5) per 16-logit sub-block
# speedup vs baseline: 1.0015x; 1.0015x over previous
.LBB0_468:
	v_add_f32_e32 v171, 0xc2200000, v0
	s_add_i32 s18, s57, 0
	v_cmp_lt_f32_e32 vcc, v173, v171
	v_mov_b32_e32 v173, 0
	s_cmp_eq_u64 vcc, exec
	v_add3_u32 v169, s18, v159, v158
	s_cbranch_scc1 .LBB0_473
	v_pk_add_f32 v[84:85], v[84:85], v[0:1] op_sel_hi:[1,0] neg_lo:[0,1] neg_hi:[0,1]
	v_exp_f32_e32 v173, v84
	v_exp_f32_e32 v175, v85
	v_pk_add_f32 v[86:87], v[86:87], v[0:1] op_sel_hi:[1,0] neg_lo:[0,1] neg_hi:[0,1]
	v_exp_f32_e32 v179, v86
	v_exp_f32_e32 v181, v87
	v_pk_add_f32 v[88:89], v[88:89], v[0:1] op_sel_hi:[1,0] neg_lo:[0,1] neg_hi:[0,1]
	v_exp_f32_e32 v182, v88
	v_exp_f32_e32 v183, v89
	v_pk_add_f32 v[90:91], v[90:91], v[0:1] op_sel_hi:[1,0] neg_lo:[0,1] neg_hi:[0,1]
	v_exp_f32_e32 v184, v90
	v_exp_f32_e32 v185, v91
	v_pk_add_f32 v[92:93], v[92:93], v[0:1] op_sel_hi:[1,0] neg_lo:[0,1] neg_hi:[0,1]
	v_exp_f32_e32 v186, v92
	v_exp_f32_e32 v187, v93
	v_pk_add_f32 v[94:95], v[94:95], v[0:1] op_sel_hi:[1,0] neg_lo:[0,1] neg_hi:[0,1]
	v_exp_f32_e32 v188, v94
	v_exp_f32_e32 v189, v95
	ds_read_b64_tr_b16 v[84:85], v169 offset:36864
	ds_read_b64_tr_b16 v[86:87], v169 offset:38016
	v_pk_add_f32 v[96:97], v[96:97], v[0:1] op_sel_hi:[1,0] neg_lo:[0,1] neg_hi:[0,1]
	v_exp_f32_e32 v96, v96
	v_cvt_pk_bf16_f32 v88, v173, v175
	v_cvt_pk_bf16_f32 v89, v179, v181
	v_cvt_pk_bf16_f32 v90, v182, v183
	v_cvt_pk_bf16_f32 v91, v184, v185
	ds_read_b64_tr_b16 v[94:95], v169 offset:38080
	ds_read_b64_tr_b16 v[92:93], v169 offset:36928
	s_waitcnt lgkmcnt(2)
	v_mfma_f32_32x32x16_bf16 v[18:33], v[84:87], v[88:91], v[18:33]
	v_exp_f32_e32 v97, v97
	v_pk_add_f32 v[98:99], v[98:99], v[0:1] op_sel_hi:[1,0] neg_lo:[0,1] neg_hi:[0,1]
	v_exp_f32_e32 v98, v98
	ds_read_b64_tr_b16 v[84:85], v169 offset:39168
	ds_read_b64_tr_b16 v[86:87], v169 offset:40320
	v_exp_f32_e32 v99, v99
	s_waitcnt lgkmcnt(2)
	v_mfma_f32_32x32x16_bf16 v[2:17], v[92:95], v[88:91], v[2:17]
	v_cvt_pk_bf16_f32 v88, v186, v187
	v_cvt_pk_bf16_f32 v89, v188, v189
	v_cvt_pk_bf16_f32 v90, v96, v97
	v_cvt_pk_bf16_f32 v91, v98, v99
	ds_read_b64_tr_b16 v[94:95], v169 offset:40384
	ds_read_b64_tr_b16 v[92:93], v169 offset:39232
	s_waitcnt lgkmcnt(2)
	v_mfma_f32_32x32x16_bf16 v[18:33], v[84:87], v[88:91], v[18:33]
	s_waitcnt lgkmcnt(0)
	v_mfma_f32_32x32x16_bf16 v[2:17], v[92:95], v[88:91], v[2:17]
	v_pk_add_f32 v[84:85], v[182:183], v[184:185]
	v_pk_add_f32 v[186:187], v[186:187], v[188:189]
	v_pk_add_f32 v[96:97], v[96:97], v[98:99]
	v_pk_add_f32 v[84:85], v[84:85], v[186:187]
	v_pk_add_f32 v[84:85], v[84:85], v[96:97]
	v_add_f32_e32 v173, v175, v173
	v_add_f32_e32 v173, v179, v173
	v_add_f32_e32 v173, v181, v173
	v_add_f32_e32 v84, v84, v85
	v_add_f32_e32 v173, v84, v173
	v_cmp_lt_f32_e32 vcc, v174, v171
	s_cmp_eq_u64 vcc, exec
	s_cbranch_scc0 .LBB0_474

.LBB0_471:
	v_pk_add_f32 v[52:53], v[52:53], v[0:1] op_sel_hi:[1,0] neg_lo:[0,1] neg_hi:[0,1]
	v_exp_f32_e32 v68, v52
	v_exp_f32_e32 v69, v53
	v_pk_add_f32 v[54:55], v[54:55], v[0:1] op_sel_hi:[1,0] neg_lo:[0,1] neg_hi:[0,1]
	v_exp_f32_e32 v70, v54
	v_exp_f32_e32 v71, v55
	v_pk_add_f32 v[56:57], v[56:57], v[0:1] op_sel_hi:[1,0] neg_lo:[0,1] neg_hi:[0,1]
	v_exp_f32_e32 v72, v56
	v_exp_f32_e32 v73, v57
	v_pk_add_f32 v[58:59], v[58:59], v[0:1] op_sel_hi:[1,0] neg_lo:[0,1] neg_hi:[0,1]
	v_exp_f32_e32 v74, v58
	v_exp_f32_e32 v75, v59
	v_pk_add_f32 v[60:61], v[60:61], v[0:1] op_sel_hi:[1,0] neg_lo:[0,1] neg_hi:[0,1]
	v_exp_f32_e32 v76, v60
	v_exp_f32_e32 v77, v61
	v_pk_add_f32 v[62:63], v[62:63], v[0:1] op_sel_hi:[1,0] neg_lo:[0,1] neg_hi:[0,1]
	v_exp_f32_e32 v78, v62
	v_exp_f32_e32 v79, v63
	ds_read_b64_tr_b16 v[52:53], v169 offset:46080
	ds_read_b64_tr_b16 v[54:55], v169 offset:47232
	v_pk_add_f32 v[64:65], v[64:65], v[0:1] op_sel_hi:[1,0] neg_lo:[0,1] neg_hi:[0,1]
	v_exp_f32_e32 v64, v64
	v_cvt_pk_bf16_f32 v56, v68, v69
	v_cvt_pk_bf16_f32 v57, v70, v71
	v_cvt_pk_bf16_f32 v58, v72, v73
	v_cvt_pk_bf16_f32 v59, v74, v75
	ds_read_b64_tr_b16 v[62:63], v169 offset:47296
	ds_read_b64_tr_b16 v[60:61], v169 offset:46144
	s_waitcnt lgkmcnt(2)
	v_mfma_f32_32x32x16_bf16 v[18:33], v[52:55], v[56:59], v[18:33]
	v_exp_f32_e32 v65, v65
	v_pk_add_f32 v[66:67], v[66:67], v[0:1] op_sel_hi:[1,0] neg_lo:[0,1] neg_hi:[0,1]
	v_exp_f32_e32 v66, v66
	ds_read_b64_tr_b16 v[52:53], v169 offset:48384
	ds_read_b64_tr_b16 v[54:55], v169 offset:49536
	v_exp_f32_e32 v67, v67
	s_waitcnt lgkmcnt(2)
	v_mfma_f32_32x32x16_bf16 v[2:17], v[60:63], v[56:59], v[2:17]
	v_cvt_pk_bf16_f32 v56, v76, v77
	v_cvt_pk_bf16_f32 v57, v78, v79
	v_cvt_pk_bf16_f32 v58, v64, v65
	v_cvt_pk_bf16_f32 v59, v66, v67
	ds_read_b64_tr_b16 v[62:63], v169 offset:49600
	ds_read_b64_tr_b16 v[60:61], v169 offset:48448
	s_waitcnt lgkmcnt(2)
	v_mfma_f32_32x32x16_bf16 v[18:33], v[52:55], v[56:59], v[18:33]
	s_waitcnt lgkmcnt(0)
	v_mfma_f32_32x32x16_bf16 v[2:17], v[60:63], v[56:59], v[2:17]
	v_pk_add_f32 v[52:53], v[68:69], v[70:71]
	v_pk_add_f32 v[72:73], v[72:73], v[74:75]
	v_pk_add_f32 v[76:77], v[76:77], v[78:79]
	v_pk_add_f32 v[64:65], v[64:65], v[66:67]
	v_pk_add_f32 v[52:53], v[52:53], v[72:73]
	v_pk_add_f32 v[76:77], v[76:77], v[64:65]
	v_pk_add_f32 v[52:53], v[52:53], v[76:77]
	v_add_f32_e32 v52, v52, v53
	v_add_f32_e32 v173, v52, v173
	v_cmp_lt_f32_e32 vcc, v170, v171
	s_cmp_eq_u64 vcc, exec
	s_cbranch_scc0 .LBB0_476
	s_branch .LBB0_477

.LBB0_474:
	v_pk_add_f32 v[68:69], v[68:69], v[0:1] op_sel_hi:[1,0] neg_lo:[0,1] neg_hi:[0,1]
	v_exp_f32_e32 v84, v68
	v_exp_f32_e32 v85, v69
	v_pk_add_f32 v[70:71], v[70:71], v[0:1] op_sel_hi:[1,0] neg_lo:[0,1] neg_hi:[0,1]
	v_exp_f32_e32 v86, v70
	v_exp_f32_e32 v87, v71
	v_pk_add_f32 v[72:73], v[72:73], v[0:1] op_sel_hi:[1,0] neg_lo:[0,1] neg_hi:[0,1]
	v_exp_f32_e32 v88, v72
	v_exp_f32_e32 v89, v73
	v_pk_add_f32 v[74:75], v[74:75], v[0:1] op_sel_hi:[1,0] neg_lo:[0,1] neg_hi:[0,1]
	v_exp_f32_e32 v90, v74
	v_exp_f32_e32 v91, v75
	v_pk_add_f32 v[76:77], v[76:77], v[0:1] op_sel_hi:[1,0] neg_lo:[0,1] neg_hi:[0,1]
	v_exp_f32_e32 v92, v76
	v_exp_f32_e32 v93, v77
	v_pk_add_f32 v[78:79], v[78:79], v[0:1] op_sel_hi:[1,0] neg_lo:[0,1] neg_hi:[0,1]
	v_exp_f32_e32 v94, v78
	v_exp_f32_e32 v95, v79
	ds_read_b64_tr_b16 v[68:69], v169 offset:41472
	ds_read_b64_tr_b16 v[70:71], v169 offset:42624
	v_pk_add_f32 v[80:81], v[80:81], v[0:1] op_sel_hi:[1,0] neg_lo:[0,1] neg_hi:[0,1]
	v_exp_f32_e32 v80, v80
	v_cvt_pk_bf16_f32 v72, v84, v85
	v_cvt_pk_bf16_f32 v73, v86, v87
	v_cvt_pk_bf16_f32 v74, v88, v89
	v_cvt_pk_bf16_f32 v75, v90, v91
	ds_read_b64_tr_b16 v[78:79], v169 offset:42688
	ds_read_b64_tr_b16 v[76:77], v169 offset:41536
	s_waitcnt lgkmcnt(2)
	v_mfma_f32_32x32x16_bf16 v[18:33], v[68:71], v[72:75], v[18:33]
	v_exp_f32_e32 v81, v81
	v_pk_add_f32 v[82:83], v[82:83], v[0:1] op_sel_hi:[1,0] neg_lo:[0,1] neg_hi:[0,1]
	v_exp_f32_e32 v82, v82
	ds_read_b64_tr_b16 v[68:69], v169 offset:43776
	ds_read_b64_tr_b16 v[70:71], v169 offset:44928
	v_exp_f32_e32 v83, v83
	s_waitcnt lgkmcnt(2)
	v_mfma_f32_32x32x16_bf16 v[2:17], v[76:79], v[72:75], v[2:17]
	v_cvt_pk_bf16_f32 v72, v92, v93
	v_cvt_pk_bf16_f32 v73, v94, v95
	v_cvt_pk_bf16_f32 v74, v80, v81
	v_cvt_pk_bf16_f32 v75, v82, v83
	ds_read_b64_tr_b16 v[78:79], v169 offset:44992
	ds_read_b64_tr_b16 v[76:77], v169 offset:43840
	s_waitcnt lgkmcnt(2)
	v_mfma_f32_32x32x16_bf16 v[18:33], v[68:71], v[72:75], v[18:33]
	s_waitcnt lgkmcnt(0)
	v_mfma_f32_32x32x16_bf16 v[2:17], v[76:79], v[72:75], v[2:17]
	v_pk_add_f32 v[68:69], v[84:85], v[86:87]
	v_pk_add_f32 v[88:89], v[88:89], v[90:91]
	v_pk_add_f32 v[92:93], v[92:93], v[94:95]
	v_pk_add_f32 v[80:81], v[80:81], v[82:83]
	v_pk_add_f32 v[68:69], v[68:69], v[88:89]
	v_pk_add_f32 v[92:93], v[92:93], v[80:81]
	v_pk_add_f32 v[68:69], v[68:69], v[92:93]
	v_add_f32_e32 v68, v68, v69
	v_add_f32_e32 v173, v68, v173
	v_cmp_lt_f32_e32 vcc, v172, v171
	s_cmp_eq_u64 vcc, exec
	s_cbranch_scc0 .LBB0_471

.LBB0_476:
	v_pk_add_f32 v[36:37], v[36:37], v[0:1] op_sel_hi:[1,0] neg_lo:[0,1] neg_hi:[0,1]
	v_exp_f32_e32 v52, v36
	v_exp_f32_e32 v53, v37
	v_pk_add_f32 v[38:39], v[38:39], v[0:1] op_sel_hi:[1,0] neg_lo:[0,1] neg_hi:[0,1]
	v_exp_f32_e32 v54, v38
	v_exp_f32_e32 v55, v39
	v_pk_add_f32 v[40:41], v[40:41], v[0:1] op_sel_hi:[1,0] neg_lo:[0,1] neg_hi:[0,1]
	v_exp_f32_e32 v56, v40
	v_exp_f32_e32 v57, v41
	v_pk_add_f32 v[42:43], v[42:43], v[0:1] op_sel_hi:[1,0] neg_lo:[0,1] neg_hi:[0,1]
	v_exp_f32_e32 v58, v42
	v_exp_f32_e32 v59, v43
	v_pk_add_f32 v[44:45], v[44:45], v[0:1] op_sel_hi:[1,0] neg_lo:[0,1] neg_hi:[0,1]
	v_exp_f32_e32 v60, v44
	v_exp_f32_e32 v61, v45
	v_pk_add_f32 v[46:47], v[46:47], v[0:1] op_sel_hi:[1,0] neg_lo:[0,1] neg_hi:[0,1]
	v_exp_f32_e32 v62, v46
	v_exp_f32_e32 v63, v47
	ds_read_b64_tr_b16 v[36:37], v169 offset:50688
	ds_read_b64_tr_b16 v[38:39], v169 offset:51840
	v_pk_add_f32 v[48:49], v[48:49], v[0:1] op_sel_hi:[1,0] neg_lo:[0,1] neg_hi:[0,1]
	v_exp_f32_e32 v48, v48
	v_cvt_pk_bf16_f32 v40, v52, v53
	v_cvt_pk_bf16_f32 v41, v54, v55
	v_cvt_pk_bf16_f32 v42, v56, v57
	v_cvt_pk_bf16_f32 v43, v58, v59
	ds_read_b64_tr_b16 v[46:47], v169 offset:51904
	ds_read_b64_tr_b16 v[44:45], v169 offset:50752
	s_waitcnt lgkmcnt(2)
	v_mfma_f32_32x32x16_bf16 v[18:33], v[36:39], v[40:43], v[18:33]
	v_exp_f32_e32 v49, v49
	v_pk_add_f32 v[50:51], v[50:51], v[0:1] op_sel_hi:[1,0] neg_lo:[0,1] neg_hi:[0,1]
	v_exp_f32_e32 v50, v50
	ds_read_b64_tr_b16 v[36:37], v169 offset:52992
	ds_read_b64_tr_b16 v[38:39], v169 offset:54144
	v_exp_f32_e32 v51, v51
	s_waitcnt lgkmcnt(2)
	v_mfma_f32_32x32x16_bf16 v[2:17], v[44:47], v[40:43], v[2:17]
	v_cvt_pk_bf16_f32 v40, v60, v61
	v_cvt_pk_bf16_f32 v41, v62, v63
	v_cvt_pk_bf16_f32 v42, v48, v49
	v_cvt_pk_bf16_f32 v43, v50, v51
	ds_read_b64_tr_b16 v[46:47], v169 offset:54208
	ds_read_b64_tr_b16 v[44:45], v169 offset:53056
	s_waitcnt lgkmcnt(2)
	v_mfma_f32_32x32x16_bf16 v[18:33], v[36:39], v[40:43], v[18:33]
	s_waitcnt lgkmcnt(0)
	v_mfma_f32_32x32x16_bf16 v[2:17], v[44:47], v[40:43], v[2:17]
	v_pk_add_f32 v[36:37], v[52:53], v[54:55]
	v_pk_add_f32 v[56:57], v[56:57], v[58:59]
	v_pk_add_f32 v[60:61], v[60:61], v[62:63]
	v_pk_add_f32 v[48:49], v[48:49], v[50:51]
	v_pk_add_f32 v[36:37], v[36:37], v[56:57]
	v_pk_add_f32 v[60:61], v[60:61], v[48:49]
	v_pk_add_f32 v[36:37], v[36:37], v[60:61]
	v_add_f32_e32 v36, v36, v37
	v_add_f32_e32 v173, v36, v173
